# attention pass 2: (x-mx)*log2e as one fma (-80 VALU per unit), on top of guard removal, scan store-address strength reduction and ret_out epilogue hoist
# speedup vs baseline: 1.0041x; 1.0005x over previous
; __global__ void __launch_bounds__(NTHR, 2) mk_fwd(Args args) {
;     ...
;     const int wave_s = __builtin_amdgcn_readfirstlane((int)(threadIdx.x >> 6));
;     const int lo = args.ph_lo, hi = args.ph_hi;
;     int pc = 0;
;     ...
; #pragma nounroll
;     for (int l = 0; l < DEPTH; ++l) {
;         const bool ovl = gridDim.x > 160;
;         if (l == 0 || !ovl) {
.LBB0_11:
	s_or_b64 exec, exec, s[0:1]
	v_readlane_b32 s2, v254, 1
	v_readlane_b32 s3, v254, 2
	s_load_dword s6, s[2:3], 0x108
	s_load_dwordx2 s[74:75], s[2:3], 0x100
	v_readfirstlane_b32 s0, v0
	s_and_b32 s1, s0, 0xffffffc0
	s_add_u32 s4, s2, 0x108
	v_writelane_b32 v254, s1, 5
	s_addc_u32 s5, s3, 0
	v_writelane_b32 v254, s4, 6
	s_waitcnt lgkmcnt(0)
	s_cmpk_gt_u32 s6, 0xa0
	s_cselect_b64 s[2:3], -1, 0
	v_writelane_b32 v254, s5, 7
	v_writelane_b32 v254, s2, 8
	s_cmpk_lt_u32 s6, 0xa1
	s_mov_b32 s5, 0
	v_writelane_b32 v254, s3, 9
	v_writelane_b32 v254, s6, 10
	s_cselect_b64 s[2:3], -1, 0
	v_writelane_b32 v254, s2, 11
	s_cmp_lt_u32 s0, 64
	s_cselect_b64 s[0:1], -1, 0
	v_writelane_b32 v254, s3, 12
	v_writelane_b32 v254, s0, 13
	s_movk_i32 s76, 0xa1
	v_mov_b32_e32 v185, 0
	v_writelane_b32 v254, s1, 14
	s_add_i32 s0, 0, 0x20160
	v_writelane_b32 v254, s0, 15
	s_add_i32 s0, 0, 0x20164
	v_writelane_b32 v254, s0, 16
	s_mov_b32 s0, 0
	v_writelane_b32 v254, s0, 17
	s_mov_b64 s[0:1], -1
	v_writelane_b32 v254, s0, 18
	v_mov_b32_e32 v208, 0x358637bd
	v_mov_b32_e32 v204, 0x260
	v_writelane_b32 v254, s1, 19
	s_mov_b64 s[0:1], 0
	v_writelane_b32 v254, s0, 20
	v_mov_b32_e32 v205, 1
	v_mov_b32_e32 v252, 0x3a27c5ac
	v_writelane_b32 v254, s1, 21
	v_writelane_b32 v254, s4, 22
	v_mov_b32_e32 v209, 0xf149f2ca
	s_mov_b32 s77, 0x3ffff
	v_writelane_b32 v254, s5, 23
	v_writelane_b32 v254, s74, 24
	s_movk_i32 s33, 0x1000
	s_mov_b32 s86, 0xf800000
	s_mov_b32 s87, 0xa001000
	s_mov_b32 s56, 0xd600000
	s_mov_b32 s54, 0xd601000
	s_mov_b32 s68, 0x2b600000
	s_mov_b32 s69, 0x3fb8aa3b
	s_mov_b64 s[88:89], 0x40000
	s_mov_b64 s[90:91], 0x80000
	s_mov_b64 s[96:97], 0xc0000
	s_mov_b64 s[84:85], 0x80
	s_mov_b64 s[94:95], 0x40080
	s_mov_b64 s[80:81], 0x80080
	s_mov_b64 s[78:79], 0xc0080
	s_mov_b64 s[70:71], 0x80180
	s_mov_b64 s[0:1], 0xb0000
	s_mov_b64 s[2:3], 0x160000
	s_mov_b64 s[36:37], 0x210000
	s_mov_b64 s[38:39], 0xb0080
	s_mov_b64 s[40:41], 0x160080
	s_mov_b64 s[42:43], 0x210080
	s_mov_b32 s62, s83
	v_writelane_b32 v254, s75, 25
	s_branch .LBB0_13

; #define LAS __attribute__((address_space(3)))
; #define LDS_WAIT() asm volatile("s_waitcnt lgkmcnt(0)" ::: "memory")
; #define MFMA32(a, b, c) __builtin_amdgcn_mfma_f32_32x32x16_bf16((a), (b), (c), 0, 0, 0)
; __device__ __forceinline__ void phase_attn(const Frame& F, const Args& a) {
;     ...
;     for (int w = vb * NWAVES + F.wave; w < 15360; w += F.NGW) {
;         const int rest = w >> 9, seq = rest % 10, g = rest / 10, sub = w & 511, h = sub >> 7, pq = sub & 127;
;         const int d = (g == 0) ? 1 : (g == 1 ? 4 : 16), Lg = SEQ / d, nqb = Lg / 32, p = pq / nqb, qb = pq % nqb;
;         const size_t base = (size_t)seq * SEQ + (size_t)p * Lg;
;         const float slope = __builtin_amdgcn_exp2f(-8.0f * (float)(g * 4 + h + 1) / 12.0f) * (float)d;
;         const bf16* Qg = QA + (size_t)g * T * 512; const bf16* Kg = KA + (size_t)g * T * 512; const bf16* Vg = VTA + (size_t)g * 512 * T;
;         f32x16 x[5]; bool tv[5]; int sc_[5];
; #pragma unroll
;         for (int kt = 0; kt < 5; ++kt) { const int s_t = 32 * qb - 64 + 32 * kt; tv[kt] = (s_t >= 0) && (s_t < Lg); sc_[kt] = tv[kt] ? s_t : 32 * qb;
; #pragma unroll
;             for (int e = 0; e < 16; ++e) x[kt][e] = 0.f; }
;         { bf16x8 ka[8], kb[8];
;           { bf16x8 qf[8];
; #pragma unroll
;             for (int ks = 0; ks < 8; ++ks) qf[ks] = *(const bf16x8*)(Qg + ((((base + 32 * qb) >> 5) * 4 + h) * 8 + ks) * 512 + lane * 8);
; #pragma unroll
;             for (int ks = 0; ks < 8; ++ks) *(LAS bf16x8*)(Pw + li * PLD + (16 * ks + 8 * hh) * 2) = qf[ks]; }
; #pragma unroll
;           for (int ks = 0; ks < 8; ++ks) { ka[ks] = *(const bf16x8*)(Kg + ((((base + sc_[0]) >> 5) * 4 + h) * 8 + ks) * 512 + lane * 8); kb[ks] = *(const bf16x8*)(Kg + ((((base + sc_[1]) >> 5) * 4 + h) * 8 + ks) * 512 + lane * 8); }
;           asm volatile("" ::: "memory");
;           LDS_WAIT(); asm volatile("" ::: "memory");
; #pragma unroll
;           for (int ks = 0; ks < 8; ++ks) { const bf16x8 q = *(const LAS bf16x8*)(Pw + li * PLD + (16 * ks + 8 * hh) * 2); x[0] = MFMA32(ka[ks], q, x[0]); x[1] = MFMA32(kb[ks], q, x[1]); }
.LBB0_1005:
	s_ashr_i32 s4, s6, 9
	s_mul_hi_i32 s5, s4, 0x66666667
	s_lshr_b32 s7, s5, 31
	s_ashr_i32 s18, s5, 2
	s_add_i32 s18, s18, s7
	s_mul_i32 s5, s18, 10
	s_sub_i32 s8, s4, s5
	s_bfe_u32 s7, s6, 0x20007
	s_and_b32 s5, s6, 0x7f
	s_add_i32 s9, s4, 9
	s_add_i32 s4, s4, -10
	s_cmp_lt_u32 s4, 10
	s_cselect_b32 s4, 4, 16
	s_cselect_b32 s10, 2, 4
	s_cmp_lt_u32 s9, 19
	s_cselect_b32 s11, 1, s4
	s_cselect_b32 s4, 0, s10
	s_lshr_b32 s9, 0x80, s4
	s_xor_b32 s10, s4, 7
	s_add_i32 s9, s9, -1
	s_lshr_b32 s82, s5, s10
	s_and_b32 s20, s9, s5
	s_sub_i32 s5, 12, s4
	s_lshl_b32 s21, s82, s5
	s_lshl_b32 s5, s18, 2
	s_or_b32 s5, s7, s5
	s_add_i32 s5, s5, 1
	v_cvt_f32_i32_e32 v0, s5
	s_ashr_i32 s9, s8, 31
	s_mov_b32 s5, 0x41400000
	s_lshl_b64 s[14:15], s[8:9], 12
	v_mul_f32_e32 v0, 0xc1000000, v0
	v_div_scale_f32 v1, s[8:9], s5, s5, v0
	v_rcp_f32_e32 v2, v1
	s_lshr_b32 s19, 0x1000, s4
	s_movk_i32 s92, 0xffe0
	s_mov_b32 s93, 0x3fffff
	v_fma_f32 v3, -v1, v2, 1.0
	v_fmac_f32_e32 v2, v3, v2
	v_div_scale_f32 v3, vcc, v0, s5, v0
	v_mul_f32_e32 v4, v3, v2
	v_fma_f32 v5, -v1, v4, v3
	v_fmac_f32_e32 v4, v5, v2
	v_fma_f32 v1, -v1, v4, v3
	v_div_fmas_f32 v1, v1, v2, v4
	v_div_fixup_f32 v0, v1, s5, v0
	s_lshl_b32 s5, s20, 5
	s_sub_i32 s22, s5, 64
	s_cmp_gt_u32 s20, 1
	s_cselect_b64 s[8:9], -1, 0
	s_cmp_lt_i32 s22, s19
	s_cselect_b64 s[16:17], -1, 0
	s_and_b64 s[28:29], s[8:9], s[16:17]
	s_and_b64 s[8:9], s[28:29], exec
	s_cselect_b32 s23, s22, s5
	s_sub_i32 s22, s5, 32
	s_cmp_lg_u32 s20, 0
	s_cselect_b64 s[8:9], -1, 0
	s_cmp_le_u32 s5, s19
	s_cselect_b64 s[16:17], -1, 0
	s_and_b64 s[74:75], s[8:9], s[16:17]
	s_and_b64 s[8:9], s[74:75], exec
	s_cselect_b32 s68, s22, s5
	s_cmp_lt_u32 s5, s19
	s_cselect_b64 s[72:73], -1, 0
	s_add_i32 s16, s5, 32
	s_cmp_lt_u32 s16, s19
	s_cselect_b64 vcc, -1, 0
	s_and_b64 s[8:9], vcc, exec
	s_cselect_b32 s22, s16, s5
	s_add_i32 s16, s5, 64
	s_cmp_lt_u32 s16, s19
	s_cselect_b64 s[26:27], -1, 0
	s_and_b64 s[8:9], s[26:27], exec
	s_cselect_b32 s44, s16, s5
	s_add_u32 s45, s14, s21
	s_addc_u32 s86, s15, 0
	v_exp_f32_e32 v0, v0
	s_add_u32 s20, s45, s5
	s_addc_u32 s21, s86, 0
	s_lshl_b32 s87, s7, 3
	s_and_b64 s[8:9], s[20:21], s[92:93]
	v_cvt_f32_ubyte0_e32 v1, s11
	s_or_b32 s8, s8, s87
	s_waitcnt vmcnt(0)
	v_mov_b32_e32 v32, 0x2800000
	v_mul_f32_e32 v120, v0, v1
	v_mad_i64_i32 v[0:1], s[16:17], s18, v32, v[138:139]
	s_lshl_b64 s[24:25], s[8:9], 10
	v_lshl_add_u64 v[16:17], v[0:1], 0, s[24:25]
	v_add_co_u32_e64 v28, s[76:77], s33, v16
	global_load_dwordx4 v[0:3], v[16:17], off
	global_load_dwordx4 v[4:7], v[16:17], off offset:1024
	global_load_dwordx4 v[8:11], v[16:17], off offset:2048
	global_load_dwordx4 v[12:15], v[16:17], off offset:3072
	v_addc_co_u32_e64 v29, s[76:77], 0, v17, s[76:77]
	global_load_dwordx4 v[16:19], v[28:29], off
	global_load_dwordx4 v[20:23], v[28:29], off offset:1024
	global_load_dwordx4 v[24:27], v[28:29], off offset:2048
	s_nop 0
	global_load_dwordx4 v[28:31], v[28:29], off offset:3072
	s_ashr_i32 s17, s23, 31
	s_add_u32 s16, s45, s23
	s_addc_u32 s17, s86, s17
	s_mul_hi_i32 s11, s18, 0x2800000
	s_mul_i32 s10, s18, 0x2800000
	s_mul_hi_i32 s8, s18, 0xa000
	s_mul_i32 s9, s18, 0xa000
	s_and_b64 s[30:31], s[16:17], s[92:93]
	s_or_b32 s30, s30, s87
	s_waitcnt vmcnt(7)
	ds_write_b128 v238, v[0:3]
	s_waitcnt vmcnt(6)
	ds_write_b128 v238, v[4:7] offset:32
	s_waitcnt vmcnt(5)
	ds_write_b128 v238, v[8:11] offset:64
	s_waitcnt vmcnt(4)
	ds_write_b128 v238, v[12:15] offset:96
	s_waitcnt vmcnt(3)
	ds_write_b128 v238, v[16:19] offset:128
	s_waitcnt vmcnt(2)
	ds_write_b128 v238, v[20:23] offset:160
	s_waitcnt vmcnt(1)
	ds_write_b128 v238, v[24:27] offset:192
	s_waitcnt vmcnt(0)
	ds_write_b128 v238, v[28:31] offset:224
	v_mad_i64_i32 v[16:17], s[18:19], s18, v32, v[142:143]
	s_ashr_i32 s19, s68, 31
	s_add_u32 s18, s45, s68
	s_addc_u32 s19, s86, s19
	s_lshl_b64 s[30:31], s[30:31], 10
	v_lshl_add_u64 v[8:9], v[16:17], 0, s[30:31]
	global_load_dwordx4 v[0:3], v[8:9], off
	s_and_b64 s[76:77], s[18:19], s[92:93]
	s_or_b32 s76, s76, s87
	s_lshl_b64 s[30:31], s[76:77], 10
	v_lshl_add_u64 v[10:11], v[16:17], 0, s[30:31]
	global_load_dwordx4 v[4:7], v[10:11], off
	global_load_dwordx4 v[18:21], v[8:9], off offset:1024
	global_load_dwordx4 v[22:25], v[10:11], off offset:1024
	global_load_dwordx4 v[26:29], v[8:9], off offset:2048
	global_load_dwordx4 v[30:33], v[10:11], off offset:2048
	global_load_dwordx4 v[34:37], v[8:9], off offset:3072
	global_load_dwordx4 v[38:41], v[10:11], off offset:3072
	v_add_co_u32_e64 v8, s[76:77], s33, v8
	s_add_u32 s22, s45, s22
	s_nop 0
	v_addc_co_u32_e64 v9, s[76:77], 0, v9, s[76:77]
	global_load_dwordx4 v[42:45], v[8:9], off
	v_add_co_u32_e64 v10, s[76:77], s33, v10
	s_addc_u32 s23, s86, 0
	s_nop 0
	v_addc_co_u32_e64 v11, s[76:77], 0, v11, s[76:77]
	global_load_dwordx4 v[46:49], v[10:11], off
	global_load_dwordx4 v[50:53], v[8:9], off offset:1024
	global_load_dwordx4 v[54:57], v[10:11], off offset:1024
	global_load_dwordx4 v[58:61], v[8:9], off offset:2048
	global_load_dwordx4 v[80:83], v[10:11], off offset:2048
	global_load_dwordx4 v[84:87], v[8:9], off offset:3072
	global_load_dwordx4 v[88:91], v[10:11], off offset:3072
	s_waitcnt lgkmcnt(0)
	ds_read_b128 v[8:11], v238
	ds_read_b128 v[92:95], v238 offset:32
	s_and_b64 s[30:31], s[22:23], s[92:93]
	s_or_b32 s30, s30, s87
	s_waitcnt vmcnt(15) lgkmcnt(1)
	v_mfma_f32_32x32x16_bf16 v[64:79], v[0:3], v[8:11], 0
	s_waitcnt vmcnt(14)
	v_mfma_f32_32x32x16_bf16 v[0:15], v[4:7], v[8:11], 0
	s_waitcnt vmcnt(13) lgkmcnt(0)
	v_mfma_f32_32x32x16_bf16 v[64:79], v[18:21], v[92:95], v[64:79]
	ds_read_b128 v[18:21], v238 offset:64
	s_waitcnt vmcnt(12)
; #define LAS __attribute__((address_space(3)))
; #define LDS_WAIT() asm volatile("s_waitcnt lgkmcnt(0)" ::: "memory")
; #define MFMA32(a, b, c) __builtin_amdgcn_mfma_f32_32x32x16_bf16((a), (b), (c), 0, 0, 0)
; __device__ __forceinline__ void phase_attn(const Frame& F, const Args& a) {
;     ...
;           for (int ks = 0; ks < 8; ++ks) { ka[ks] = *(const bf16x8*)(Kg + ((((base + sc_[0]) >> 5) * 4 + h) * 8 + ks) * 512 + lane * 8); kb[ks] = *(const bf16x8*)(Kg + ((((base + sc_[1]) >> 5) * 4 + h) * 8 + ks) * 512 + lane * 8); }
;           asm volatile("" ::: "memory");
;           LDS_WAIT(); asm volatile("" ::: "memory");
; #pragma unroll
;           for (int ks = 0; ks < 8; ++ks) { const bf16x8 q = *(const LAS bf16x8*)(Pw + li * PLD + (16 * ks + 8 * hh) * 2); x[0] = MFMA32(ka[ks], q, x[0]); x[1] = MFMA32(kb[ks], q, x[1]); }
; #pragma unroll
;           for (int ks = 0; ks < 8; ++ks) { ka[ks] = *(const bf16x8*)(Kg + ((((base + sc_[2]) >> 5) * 4 + h) * 8 + ks) * 512 + lane * 8); kb[ks] = *(const bf16x8*)(Kg + ((((base + sc_[3]) >> 5) * 4 + h) * 8 + ks) * 512 + lane * 8); }
;           asm volatile("" ::: "memory");
; #pragma unroll
;           for (int ks = 0; ks < 8; ++ks) { const bf16x8 q = *(const LAS bf16x8*)(Pw + li * PLD + (16 * ks + 8 * hh) * 2); x[2] = MFMA32(ka[ks], q, x[2]); x[3] = MFMA32(kb[ks], q, x[3]); }
; #pragma unroll
;           for (int ks = 0; ks < 8; ++ks) ka[ks] = *(const bf16x8*)(Kg + ((((base + sc_[4]) >> 5) * 4 + h) * 8 + ks) * 512 + lane * 8);
;           asm volatile("" ::: "memory");
; #pragma unroll
;           for (int ks = 0; ks < 8; ++ks) { const bf16x8 q = *(const LAS bf16x8*)(Pw + li * PLD + (16 * ks + 8 * hh) * 2); x[4] = MFMA32(ka[ks], q, x[4]); }
	v_mfma_f32_32x32x16_bf16 v[0:15], v[22:25], v[92:95], v[0:15]
	s_waitcnt vmcnt(11) lgkmcnt(0)
	v_mfma_f32_32x32x16_bf16 v[64:79], v[26:29], v[18:21], v[64:79]
	s_waitcnt vmcnt(10)
	v_mfma_f32_32x32x16_bf16 v[0:15], v[30:33], v[18:21], v[0:15]
	ds_read_b128 v[18:21], v238 offset:96
	v_lshl_add_u64 v[30:31], v[16:17], 0, s[24:25]
	s_lshl_b64 s[24:25], s[30:31], 10
	v_lshl_add_u64 v[32:33], v[16:17], 0, s[24:25]
	s_add_u32 s30, s45, s44
	s_addc_u32 s31, s86, 0
	s_and_b64 s[24:25], s[30:31], s[92:93]
	s_waitcnt vmcnt(9) lgkmcnt(0)
	v_mfma_f32_32x32x16_bf16 v[64:79], v[34:37], v[18:21], v[64:79]
	s_or_b32 s24, s24, s87
	s_lshl_b64 s[24:25], s[24:25], 10
	s_mul_i32 s44, s7, 0x1400
	s_waitcnt vmcnt(8)
	v_mfma_f32_32x32x16_bf16 v[0:15], v[38:41], v[18:21], v[0:15]
	ds_read_b128 v[18:21], v238 offset:128
	s_waitcnt vmcnt(7) lgkmcnt(0)
	v_mfma_f32_32x32x16_bf16 v[64:79], v[42:45], v[18:21], v[64:79]
	s_waitcnt vmcnt(6)
	v_mfma_f32_32x32x16_bf16 v[0:15], v[46:49], v[18:21], v[0:15]
	ds_read_b128 v[18:21], v238 offset:160
	s_waitcnt vmcnt(5) lgkmcnt(0)
	v_mfma_f32_32x32x16_bf16 v[64:79], v[50:53], v[18:21], v[64:79]
	s_waitcnt vmcnt(4)
	v_mfma_f32_32x32x16_bf16 v[0:15], v[54:57], v[18:21], v[0:15]
	ds_read_b128 v[18:21], v238 offset:192
	s_waitcnt vmcnt(3) lgkmcnt(0)
	v_mfma_f32_32x32x16_bf16 v[64:79], v[58:61], v[18:21], v[64:79]
	s_waitcnt vmcnt(2)
	v_mfma_f32_32x32x16_bf16 v[0:15], v[80:83], v[18:21], v[0:15]
	ds_read_b128 v[18:21], v238 offset:224
	s_waitcnt vmcnt(1) lgkmcnt(0)
	v_mfma_f32_32x32x16_bf16 v[64:79], v[84:87], v[18:21], v[64:79]
	s_waitcnt vmcnt(0)
	v_mfma_f32_32x32x16_bf16 v[0:15], v[88:91], v[18:21], v[0:15]
	global_load_dwordx4 v[18:21], v[30:31], off
	global_load_dwordx4 v[22:25], v[32:33], off
	global_load_dwordx4 v[26:29], v[30:31], off offset:1024
	global_load_dwordx4 v[80:83], v[32:33], off offset:1024
	global_load_dwordx4 v[84:87], v[30:31], off offset:2048
	global_load_dwordx4 v[88:91], v[32:33], off offset:2048
	global_load_dwordx4 v[92:95], v[30:31], off offset:3072
	global_load_dwordx4 v[96:99], v[32:33], off offset:3072
	v_add_co_u32_e64 v30, s[76:77], s33, v30
	s_nop 0
	v_fma_f32 v64, -v120, v148, v64
	v_addc_co_u32_e64 v31, s[76:77], 0, v31, s[76:77]
	global_load_dwordx4 v[100:103], v[30:31], off
	v_add_co_u32_e64 v32, s[76:77], s33, v32
	v_fma_f32 v0, -v120, v164, v0
	s_nop 0
	v_addc_co_u32_e64 v33, s[76:77], 0, v33, s[76:77]
	global_load_dwordx4 v[104:107], v[32:33], off
	global_load_dwordx4 v[108:111], v[30:31], off offset:1024
	global_load_dwordx4 v[112:115], v[32:33], off offset:1024
	global_load_dwordx4 v[116:119], v[30:31], off offset:2048
	global_load_dwordx4 v[122:125], v[32:33], off offset:2048
	global_load_dwordx4 v[126:129], v[30:31], off offset:3072
	global_load_dwordx4 v[130:133], v[32:33], off offset:3072
	ds_read_b128 v[30:33], v238
	ds_read_b128 v[240:243], v238 offset:32
	s_waitcnt vmcnt(15) lgkmcnt(1)
	v_mfma_f32_32x32x16_bf16 v[48:63], v[18:21], v[30:33], 0
	ds_read_b128 v[18:21], v238 offset:64
	v_cndmask_b32_e64 v251, v209, v0, s[74:75]
	v_fma_f32 v0, -v120, v165, v1
	v_fma_f32 v1, -v120, v166, v2
	v_cndmask_b32_e64 v249, v209, v1, s[74:75]
	v_fma_f32 v1, -v120, v167, v3
	v_cndmask_b32_e64 v248, v209, v1, s[74:75]
	s_waitcnt vmcnt(14)
	v_mfma_f32_32x32x16_bf16 v[32:47], v[22:25], v[30:33], 0
	v_fma_f32 v1, -v120, v168, v4
	v_cndmask_b32_e64 v247, v209, v1, s[74:75]
	v_fma_f32 v1, -v120, v169, v5
	v_cndmask_b32_e64 v245, v209, v1, s[74:75]
	v_fma_f32 v1, -v120, v170, v6
	v_cndmask_b32_e64 v244, v209, v1, s[74:75]
	v_fma_f32 v1, -v120, v171, v7
	s_waitcnt vmcnt(13) lgkmcnt(1)
	v_mfma_f32_32x32x16_bf16 v[48:63], v[26:29], v[240:243], v[48:63]
	v_cndmask_b32_e64 v250, v209, v0, s[74:75]
	s_waitcnt vmcnt(12)
	v_mfma_f32_32x32x16_bf16 v[32:47], v[80:83], v[240:243], v[32:47]
	v_cndmask_b32_e64 v243, v209, v1, s[74:75]
	v_fma_f32 v1, -v120, v172, v8
	v_cndmask_b32_e64 v241, v209, v1, s[74:75]
	v_fma_f32 v1, -v120, v173, v9
	v_cndmask_b32_e64 v239, v209, v1, s[74:75]
	v_fma_f32 v1, -v120, v174, v10
	v_cndmask_b32_e64 v145, v209, v1, s[74:75]
	s_waitcnt vmcnt(11) lgkmcnt(0)
	v_mfma_f32_32x32x16_bf16 v[48:63], v[84:87], v[18:21], v[48:63]
	v_fma_f32 v1, -v120, v175, v11
	s_waitcnt vmcnt(10)
	v_mfma_f32_32x32x16_bf16 v[32:47], v[88:91], v[18:21], v[32:47]
	ds_read_b128 v[18:21], v238 offset:96
	s_waitcnt vmcnt(9) lgkmcnt(0)
	v_mfma_f32_32x32x16_bf16 v[48:63], v[92:95], v[18:21], v[48:63]
	s_waitcnt vmcnt(8)
	v_mfma_f32_32x32x16_bf16 v[32:47], v[96:99], v[18:21], v[32:47]
	ds_read_b128 v[18:21], v238 offset:128
	s_waitcnt vmcnt(7) lgkmcnt(0)
	v_mfma_f32_32x32x16_bf16 v[48:63], v[100:103], v[18:21], v[48:63]
	s_waitcnt vmcnt(6)
	v_mfma_f32_32x32x16_bf16 v[32:47], v[104:107], v[18:21], v[32:47]
	ds_read_b128 v[18:21], v238 offset:160
	s_waitcnt vmcnt(5) lgkmcnt(0)
	v_mfma_f32_32x32x16_bf16 v[48:63], v[108:111], v[18:21], v[48:63]
	s_waitcnt vmcnt(4)
	v_mfma_f32_32x32x16_bf16 v[32:47], v[112:115], v[18:21], v[32:47]
	ds_read_b128 v[18:21], v238 offset:192
	s_waitcnt vmcnt(3) lgkmcnt(0)
	v_mfma_f32_32x32x16_bf16 v[48:63], v[116:119], v[18:21], v[48:63]
	s_waitcnt vmcnt(2)
	v_mfma_f32_32x32x16_bf16 v[32:47], v[122:125], v[18:21], v[32:47]
	ds_read_b128 v[18:21], v238 offset:224
	s_waitcnt vmcnt(1) lgkmcnt(0)
	v_mfma_f32_32x32x16_bf16 v[48:63], v[126:129], v[18:21], v[48:63]
	s_waitcnt vmcnt(0)
; #define LAS __attribute__((address_space(3)))
; #define LDS_WAIT() asm volatile("s_waitcnt lgkmcnt(0)" ::: "memory")
; #define MFMA32(a, b, c) __builtin_amdgcn_mfma_f32_32x32x16_bf16((a), (b), (c), 0, 0, 0)
; #define ATT_VLOAD(VF, dt_) do { _Pragma("unroll") for (int kt = 0; kt < 5; ++kt) _Pragma("unroll") for (int k2 = 0; k2 < 2; ++k2) \
;             VF[kt][k2] = ldfrag(Vg + ((((size_t)(h * 4 + (dt_)) * (T / 32) + ((base + sc_[kt]) >> 5)) * 2 + k2) * 512), (unsigned)lane * 16u); } while (0)
; __device__ __forceinline__ void phase_attn(const Frame& F, const Args& a) {
;     ...
;           for (int ks = 0; ks < 8; ++ks) { const bf16x8 q = *(const LAS bf16x8*)(Pw + li * PLD + (16 * ks + 8 * hh) * 2); x[4] = MFMA32(ka[ks], q, x[4]); }
;           LDS_WAIT(); asm volatile("" ::: "memory");
;         }
;     ...
;         bf16x8 vfA[5][2], vfB[5][2], vfC[5][2];
;         ATT_VLOAD(vfA, 0); asm volatile("" ::: "memory");
;         float mx = -1e30f;
; #pragma unroll
;         for (int kt = 0; kt < 5; ++kt)
; #pragma unroll
;             for (int e = 0; e < 16; ++e) { const int j = (e & 3) + 8 * (e >> 2) + 4 * hh; const int rel = 32 * kt - 64 + j - li; const int ar = rel < 0 ? -rel : rel;
;                 const bool ok = tv[kt] && ar <= 64; const float sv = ok ? (x[kt][e] - slope * (float)ar) : -1e30f; x[kt][e] = sv; mx = fmaxf(mx, sv); }
	v_mfma_f32_32x32x16_bf16 v[32:47], v[130:133], v[18:21], v[32:47]
	v_lshl_add_u64 v[20:21], v[16:17], 0, s[24:25]
	global_load_dwordx4 v[16:19], v[20:21], off
	global_load_dwordx4 v[80:83], v[20:21], off offset:1024
	global_load_dwordx4 v[84:87], v[20:21], off offset:2048
	global_load_dwordx4 v[88:91], v[20:21], off offset:3072
	v_add_co_u32_e64 v20, s[76:77], s33, v20
	v_readlane_b32 s24, v255, 7
	s_nop 0
	v_addc_co_u32_e64 v21, s[76:77], 0, v21, s[76:77]
	global_load_dwordx4 v[92:95], v[20:21], off
	global_load_dwordx4 v[96:99], v[20:21], off offset:1024
	global_load_dwordx4 v[100:103], v[20:21], off offset:2048
	global_load_dwordx4 v[104:107], v[20:21], off offset:3072
	ds_read_b128 v[20:23], v238
	ds_read_b128 v[108:111], v238 offset:32
	s_waitcnt vmcnt(7) lgkmcnt(1)
	v_mfma_f32_32x32x16_bf16 v[16:31], v[16:19], v[20:23], 0
	s_add_u32 s10, s24, s10
	v_readlane_b32 s24, v255, 9
	s_addc_u32 s11, s24, s11
	s_lshr_b64 s[16:17], s[16:17], 5
	s_add_u32 s24, s16, s44
	s_addc_u32 s25, s17, 0
	s_lshl_b64 s[24:25], s[24:25], 11
	s_waitcnt vmcnt(6) lgkmcnt(0)
	v_mfma_f32_32x32x16_bf16 v[16:31], v[80:83], v[108:111], v[16:31]
	ds_read_b128 v[80:83], v238 offset:64
	s_add_u32 s24, s10, s24
	s_addc_u32 s25, s11, s25
	s_mov_b64 s[76:77], s[24:25]
	s_add_u32 s24, s24, 0x400
	s_addc_u32 s25, s25, 0
	s_lshr_b64 s[18:19], s[18:19], 5
	s_waitcnt vmcnt(5) lgkmcnt(0)
	v_mfma_f32_32x32x16_bf16 v[16:31], v[84:87], v[80:83], v[16:31]
	ds_read_b128 v[80:83], v238 offset:96
	v_cndmask_b32_e64 v132, v209, v1, s[74:75]
	v_fma_f32 v1, -v120, v176, v12
	v_cndmask_b32_e64 v127, v209, v1, s[74:75]
	v_fma_f32 v1, -v120, v177, v13
	s_waitcnt vmcnt(4) lgkmcnt(0)
	v_mfma_f32_32x32x16_bf16 v[16:31], v[88:91], v[80:83], v[16:31]
	ds_read_b128 v[80:83], v238 offset:128
	s_waitcnt vmcnt(3) lgkmcnt(0)
	v_mfma_f32_32x32x16_bf16 v[16:31], v[92:95], v[80:83], v[16:31]
	ds_read_b128 v[80:83], v238 offset:160
	s_waitcnt vmcnt(2) lgkmcnt(0)
	v_mfma_f32_32x32x16_bf16 v[16:31], v[96:99], v[80:83], v[16:31]
	ds_read_b128 v[80:83], v238 offset:192
	s_waitcnt vmcnt(1) lgkmcnt(0)
	v_mfma_f32_32x32x16_bf16 v[16:31], v[100:103], v[80:83], v[16:31]
	ds_read_b128 v[80:83], v238 offset:224
	s_waitcnt lgkmcnt(0)
	s_waitcnt vmcnt(0) lgkmcnt(0)
	v_mfma_f32_32x32x16_bf16 v[16:31], v[104:107], v[80:83], v[16:31]
	v_lshl_add_u64 v[80:81], s[76:77], 0, v[136:137]
	global_load_dwordx4 v[80:83], v[80:81], off
	s_nop 0
	v_lshl_add_u64 v[84:85], s[24:25], 0, v[136:137]
	s_add_u32 s24, s18, s44
	s_addc_u32 s25, s19, 0
	s_lshl_b64 s[24:25], s[24:25], 11
	s_add_u32 s24, s10, s24
	s_addc_u32 s25, s11, s25
	s_mov_b64 s[76:77], s[24:25]
	s_add_u32 s24, s24, 0x400
	global_load_dwordx4 v[84:87], v[84:85], off
	s_addc_u32 s25, s25, 0
	v_lshl_add_u64 v[88:89], s[76:77], 0, v[136:137]
	global_load_dwordx4 v[88:91], v[88:89], off
	s_nop 0
	v_lshl_add_u64 v[92:93], s[24:25], 0, v[136:137]
	s_lshr_b64 s[24:25], s[20:21], 5
	s_add_u32 s20, s24, s44
	s_addc_u32 s21, s25, 0
	s_lshl_b64 s[20:21], s[20:21], 11
	s_add_u32 s20, s10, s20
	s_addc_u32 s21, s11, s21
	s_mov_b64 s[76:77], s[20:21]
	s_add_u32 s20, s20, 0x400
	global_load_dwordx4 v[92:95], v[92:93], off
	s_addc_u32 s21, s21, 0
	v_lshl_add_u64 v[96:97], s[76:77], 0, v[136:137]
	global_load_dwordx4 v[100:103], v[96:97], off
	s_lshr_b64 s[22:23], s[22:23], 5
	v_lshl_add_u64 v[96:97], s[20:21], 0, v[136:137]
	s_add_u32 s20, s22, s44
	s_addc_u32 s21, s23, 0
	s_lshl_b64 s[20:21], s[20:21], 11
	s_add_u32 s20, s10, s20
	s_addc_u32 s21, s11, s21
	s_mov_b64 s[76:77], s[20:21]
	s_add_u32 s20, s20, 0x400
	global_load_dwordx4 v[96:99], v[96:97], off
	s_addc_u32 s21, s21, 0
	v_lshl_add_u64 v[104:105], s[76:77], 0, v[136:137]
	global_load_dwordx4 v[112:115], v[104:105], off
	s_nop 0
	v_lshl_add_u64 v[104:105], s[20:21], 0, v[136:137]
	s_lshr_b64 s[20:21], s[30:31], 5
	s_add_u32 s30, s20, s44
	s_addc_u32 s31, s21, 0
	s_lshl_b64 s[30:31], s[30:31], 11
	s_add_u32 s30, s10, s30
	s_addc_u32 s31, s11, s31
	s_mov_b64 s[76:77], s[30:31]
	s_add_u32 s30, s30, 0x400
	global_load_dwordx4 v[104:107], v[104:105], off
	s_addc_u32 s31, s31, 0
	v_lshl_add_u64 v[108:109], s[76:77], 0, v[136:137]
	global_load_dwordx4 v[116:119], v[108:109], off
	s_nop 0
	v_lshl_add_u64 v[108:109], s[30:31], 0, v[136:137]
	v_readlane_b32 s30, v255, 13
	v_readlane_b32 s31, v255, 14
	s_and_b64 s[76:77], s[28:29], s[30:31]
	v_readlane_b32 s30, v255, 31
	v_readlane_b32 s31, v255, 32
	v_cndmask_b32_e64 v144, v209, v64, s[76:77]
	s_and_b64 s[76:77], s[28:29], s[30:31]
	v_fma_f32 v64, -v120, v149, v65
	v_cndmask_b32_e64 v133, v209, v64, s[76:77]
	s_mov_b32 s30, 0xf149f2ca
	v_max3_f32 v64, v144, s30, v133
	v_readlane_b32 s30, v255, 33
	v_readlane_b32 s31, v255, 34
	s_and_b64 s[76:77], s[28:29], s[30:31]
	v_readlane_b32 s30, v255, 35
	v_fma_f32 v65, -v120, v150, v66
	v_readlane_b32 s31, v255, 36
	v_cndmask_b32_e64 v134, v209, v65, s[76:77]
	s_and_b64 s[76:77], s[28:29], s[30:31]
	v_readlane_b32 s30, v255, 37
	v_fma_f32 v65, -v120, v151, v67
	v_readlane_b32 s31, v255, 38
	v_cndmask_b32_e64 v131, v209, v65, s[76:77]
	s_and_b64 s[76:77], s[28:29], s[30:31]
	v_readlane_b32 s30, v255, 39
	v_fma_f32 v65, -v120, v152, v68
	v_readlane_b32 s31, v255, 40
	v_cndmask_b32_e64 v130, v209, v65, s[76:77]
	s_and_b64 s[76:77], s[28:29], s[30:31]
	v_readlane_b32 s30, v255, 41
	v_fma_f32 v65, -v120, v153, v69
	v_readlane_b32 s31, v255, 42
	v_cndmask_b32_e64 v128, v209, v65, s[76:77]
	s_and_b64 s[76:77], s[28:29], s[30:31]
	v_readlane_b32 s30, v255, 43
	v_fma_f32 v65, -v120, v154, v70
	v_readlane_b32 s31, v255, 44
	v_cndmask_b32_e64 v126, v209, v65, s[76:77]
	s_and_b64 s[76:77], s[28:29], s[30:31]
	v_readlane_b32 s30, v255, 45
; __device__ __forceinline__ void phase_attn(const Frame& F, const Args& a) {
;     ...
;         for (int kt = 0; kt < 5; ++kt)
; #pragma unroll
;             for (int e = 0; e < 16; ++e) { const int j = (e & 3) + 8 * (e >> 2) + 4 * hh; const int rel = 32 * kt - 64 + j - li; const int ar = rel < 0 ? -rel : rel;
;                 const bool ok = tv[kt] && ar <= 64; const float sv = ok ? (x[kt][e] - slope * (float)ar) : -1e30f; x[kt][e] = sv; mx = fmaxf(mx, sv); }
	v_fma_f32 v65, -v120, v155, v71
	v_readlane_b32 s31, v255, 46
	v_cndmask_b32_e64 v125, v209, v65, s[76:77]
	s_and_b64 s[76:77], s[28:29], s[30:31]
	v_readlane_b32 s30, v255, 47
	v_fma_f32 v65, -v120, v156, v72
	v_readlane_b32 s31, v255, 48
	v_cndmask_b32_e64 v124, v209, v65, s[76:77]
	s_and_b64 s[76:77], s[28:29], s[30:31]
	v_readlane_b32 s30, v255, 49
	v_fma_f32 v65, -v120, v157, v73
	v_readlane_b32 s31, v255, 50
	v_cndmask_b32_e64 v123, v209, v65, s[76:77]
	s_and_b64 s[76:77], s[28:29], s[30:31]
	v_readlane_b32 s30, v255, 51
	v_fma_f32 v65, -v120, v158, v74
	v_readlane_b32 s31, v255, 52
	v_cndmask_b32_e64 v122, v209, v65, s[76:77]
	s_and_b64 s[76:77], s[28:29], s[30:31]
	v_fma_f32 v65, -v120, v159, v75
	v_cndmask_b32_e64 v74, v209, v65, s[76:77]
	v_fma_f32 v65, -v120, v160, v76
	v_cndmask_b32_e64 v76, v209, v1, s[74:75]
	v_fma_f32 v1, -v120, v178, v14
	v_cndmask_b32_e64 v68, v209, v1, s[74:75]
	v_fma_f32 v1, -v120, v179, v15
	v_readlane_b32 s30, v254, 60
	v_cndmask_b32_e64 v242, v209, v1, s[74:75]
	v_fma_f32 v1, -v120, v180, v48
	v_readlane_b32 s31, v254, 61
	v_cndmask_b32_e64 v240, v209, v1, s[72:73]
	v_fma_f32 v1, -v120, v181, v49
	s_and_b64 s[76:77], s[28:29], s[30:31]
	v_readlane_b32 s30, v255, 15
	v_cndmask_b32_e64 v184, v209, v1, s[72:73]
	v_fma_f32 v1, -v120, v182, v50
	v_readlane_b32 s31, v255, 16
	v_cndmask_b32_e64 v135, v209, v1, s[72:73]
	v_fma_f32 v1, -v120, v183, v51
	v_cndmask_b32_e64 v72, v209, v65, s[76:77]
	s_and_b64 s[76:77], s[28:29], s[30:31]
	v_fma_f32 v65, -v120, v161, v77
	v_cndmask_b32_e64 v129, v209, v1, s[72:73]
	v_fma_f32 v1, -v120, v186, v52
	v_cndmask_b32_e64 v69, v209, v65, s[76:77]
	v_fma_f32 v65, -v120, v162, v78
	v_cndmask_b32_e64 v78, v209, v1, s[72:73]
	v_fma_f32 v1, -v120, v188, v53
	v_cndmask_b32_e64 v121, v209, v1, s[72:73]
	v_fma_f32 v1, -v120, v189, v54
	v_fma_f32 v66, -v120, v163, v79
	v_cndmask_b32_e64 v79, v209, v1, s[72:73]
	v_fma_f32 v1, -v120, v190, v55
	v_max3_f32 v64, v64, v134, v131
	v_readlane_b32 s30, v255, 17
	v_cndmask_b32_e64 v77, v209, v1, s[72:73]
	v_fma_f32 v1, -v120, v191, v56
	v_max3_f32 v64, v64, v130, v128
	v_readlane_b32 s31, v255, 18
	v_cndmask_b32_e64 v75, v209, v1, s[72:73]
	v_fma_f32 v1, -v120, v192, v57
	v_max3_f32 v64, v64, v126, v125
	s_and_b64 s[76:77], s[28:29], s[30:31]
	v_readlane_b32 s30, v255, 19
	v_cndmask_b32_e64 v73, v209, v1, s[72:73]
	v_fma_f32 v1, -v120, v193, v58
	v_max3_f32 v64, v64, v124, v123
	v_readlane_b32 s31, v255, 20
	v_cndmask_b32_e64 v71, v209, v1, s[72:73]
	v_fma_f32 v1, -v120, v194, v59
	v_max3_f32 v64, v64, v122, v74
	v_cndmask_b32_e64 v65, v209, v65, s[76:77]
	s_and_b64 s[76:77], s[28:29], s[30:31]
	v_cndmask_b32_e64 v70, v209, v1, s[72:73]
	v_fma_f32 v1, -v120, v195, v60
	v_max3_f32 v64, v64, v72, v69
	v_cndmask_b32_e64 v246, v209, v66, s[76:77]
	v_cndmask_b32_e64 v67, v209, v1, s[72:73]
	v_fma_f32 v1, -v120, v196, v61
	v_max3_f32 v64, v64, v65, v246
	v_cndmask_b32_e64 v66, v209, v1, s[72:73]
	v_fma_f32 v1, -v120, v197, v62
	v_max3_f32 v0, v64, v251, v250
	v_cndmask_b32_e64 v64, v209, v1, s[72:73]
	v_fma_f32 v1, -v120, v198, v63
	v_cndmask_b32_e64 v62, v209, v1, s[72:73]
	v_fma_f32 v1, -v120, v199, v32
	v_cndmask_b32_e32 v61, v209, v1, vcc
	v_fma_f32 v1, -v120, v200, v33
	v_cndmask_b32_e32 v58, v209, v1, vcc
	v_fma_f32 v1, -v120, v201, v34
	v_cndmask_b32_e32 v57, v209, v1, vcc
	v_fma_f32 v1, -v120, v202, v35
	v_cndmask_b32_e32 v55, v209, v1, vcc
	v_fma_f32 v1, -v120, v203, v36
	v_cndmask_b32_e32 v54, v209, v1, vcc
	v_fma_f32 v1, -v120, v211, v37
	v_max3_f32 v0, v0, v249, v248
	v_cndmask_b32_e32 v53, v209, v1, vcc
	v_fma_f32 v1, -v120, v212, v38
	v_max3_f32 v0, v0, v247, v245
	v_cndmask_b32_e32 v52, v209, v1, vcc
	v_fma_f32 v1, -v120, v213, v39
	v_max3_f32 v0, v0, v244, v243
	v_cndmask_b32_e32 v51, v209, v1, vcc
	v_fma_f32 v1, -v120, v214, v40
	v_max3_f32 v0, v0, v241, v239
	v_cndmask_b32_e32 v50, v209, v1, vcc
	v_fma_f32 v1, -v120, v215, v41
	v_max3_f32 v0, v0, v145, v132
	v_cndmask_b32_e32 v49, v209, v1, vcc
	v_fma_f32 v1, -v120, v216, v42
	v_max3_f32 v0, v0, v127, v76
	v_cndmask_b32_e32 v48, v209, v1, vcc
	v_fma_f32 v1, -v120, v217, v43
	v_max3_f32 v0, v0, v68, v242
	v_cndmask_b32_e32 v43, v209, v1, vcc
	v_fma_f32 v1, -v120, v218, v44
	v_max3_f32 v0, v0, v240, v184
	v_cndmask_b32_e32 v42, v209, v1, vcc
	v_fma_f32 v1, -v120, v219, v45
	v_max3_f32 v0, v0, v135, v129
	v_cndmask_b32_e32 v41, v209, v1, vcc
	v_fma_f32 v1, -v120, v220, v46
	v_readlane_b32 s28, v255, 21
	v_max3_f32 v0, v0, v78, v121
	v_cndmask_b32_e32 v40, v209, v1, vcc
	v_fma_f32 v1, -v120, v221, v47
	v_readlane_b32 s29, v255, 22
	v_max3_f32 v0, v0, v79, v77
	v_cndmask_b32_e32 v38, v209, v1, vcc
	s_and_b64 vcc, s[26:27], s[28:29]
	v_readlane_b32 s28, v255, 23
	v_max3_f32 v0, v0, v75, v73
	v_fma_f32 v1, -v120, v222, v16
	v_readlane_b32 s29, v255, 24
	v_max3_f32 v0, v0, v71, v70
	v_cndmask_b32_e32 v39, v209, v1, vcc
	s_and_b64 vcc, s[26:27], s[28:29]
	v_readlane_b32 s28, v255, 25
	v_max3_f32 v0, v0, v67, v66
	v_fma_f32 v1, -v120, v223, v17
	v_readlane_b32 s29, v255, 26
	v_max3_f32 v0, v0, v64, v62
	v_cndmask_b32_e32 v37, v209, v1, vcc
	s_and_b64 vcc, s[26:27], s[28:29]
	v_fma_f32 v1, -v120, v224, v18
	v_max3_f32 v0, v0, v61, v58
	v_cndmask_b32_e32 v36, v209, v1, vcc
	s_and_b64 vcc, s[26:27], s[46:47]
	v_fma_f32 v1, -v120, v225, v19
	v_max3_f32 v0, v0, v57, v55
	v_cndmask_b32_e32 v35, v209, v1, vcc
	s_and_b64 vcc, s[26:27], s[48:49]
	v_fma_f32 v1, -v120, v226, v20
	v_max3_f32 v0, v0, v54, v53
	v_cndmask_b32_e32 v34, v209, v1, vcc
	s_and_b64 vcc, s[26:27], s[50:51]
	v_fma_f32 v1, -v120, v227, v21
	v_max3_f32 v0, v0, v52, v51
	v_cndmask_b32_e32 v33, v209, v1, vcc
; __device__ __forceinline__ float fexp(float x) { return __builtin_amdgcn_exp2f(x * 1.44269504089f); }
; __device__ __forceinline__ float shfl_xor_(float v, int m) { return __builtin_bit_cast(float, __builtin_amdgcn_ds_bpermute((lane_id() ^ m) << 2, __builtin_bit_cast(int, v))); }
; __device__ __forceinline__ void phase_attn(const Frame& F, const Args& a) {
;     ...
;             for (int e = 0; e < 16; ++e) { const int j = (e & 3) + 8 * (e >> 2) + 4 * hh; const int rel = 32 * kt - 64 + j - li; const int ar = rel < 0 ? -rel : rel;
;                 const bool ok = tv[kt] && ar <= 64; const float sv = ok ? (x[kt][e] - slope * (float)ar) : -1e30f; x[kt][e] = sv; mx = fmaxf(mx, sv); }
;         mx = fmaxf(mx, shfl_xor_(mx, 32));
;         float sum = 0.f;
; #pragma unroll
;         for (int kt = 0; kt < 5; ++kt)
; #pragma unroll
;             for (int e = 0; e < 16; ++e) { const float pv = (x[kt][e] > -1e29f) ? fexp(x[kt][e] - mx) : 0.f; x[kt][e] = pv; sum += pv; }
	s_and_b64 vcc, s[26:27], s[52:53]
	v_fma_f32 v1, -v120, v228, v22
	v_max3_f32 v0, v0, v50, v49
	v_cndmask_b32_e32 v32, v209, v1, vcc
	s_and_b64 vcc, s[26:27], s[54:55]
	v_fma_f32 v1, -v120, v229, v23
	v_max3_f32 v0, v0, v48, v43
	v_cndmask_b32_e32 v22, v209, v1, vcc
	s_and_b64 vcc, s[26:27], s[56:57]
	v_fma_f32 v1, -v120, v230, v24
	v_max3_f32 v0, v0, v42, v41
	v_cndmask_b32_e32 v20, v209, v1, vcc
	s_and_b64 vcc, s[26:27], s[58:59]
	v_fma_f32 v1, -v120, v231, v25
	v_max3_f32 v0, v0, v40, v38
	v_cndmask_b32_e32 v19, v209, v1, vcc
	s_and_b64 vcc, s[26:27], s[60:61]
	v_fma_f32 v1, -v120, v232, v26
	v_max3_f32 v0, v0, v39, v37
	v_cndmask_b32_e32 v18, v209, v1, vcc
	s_and_b64 vcc, s[26:27], s[62:63]
	v_fma_f32 v1, -v120, v233, v27
	v_max3_f32 v0, v0, v36, v35
	v_cndmask_b32_e32 v16, v209, v1, vcc
	s_and_b64 vcc, s[26:27], s[64:65]
	v_fma_f32 v1, -v120, v234, v28
	v_max3_f32 v0, v0, v34, v33
	v_cndmask_b32_e32 v15, v209, v1, vcc
	s_and_b64 vcc, s[26:27], s[66:67]
	v_fma_f32 v1, -v120, v235, v29
	v_max3_f32 v0, v0, v32, v22
	v_cndmask_b32_e32 v13, v209, v1, vcc
	s_and_b64 vcc, s[26:27], s[34:35]
	v_fma_f32 v1, -v120, v236, v30
	v_max3_f32 v0, v0, v20, v19
	v_cndmask_b32_e32 v12, v209, v1, vcc
	s_and_b64 vcc, s[26:27], s[70:71]
	v_fma_f32 v1, -v120, v237, v31
	global_load_dwordx4 v[108:111], v[108:109], off
	v_max3_f32 v0, v0, v18, v16
	v_cndmask_b32_e32 v21, v209, v1, vcc
	v_mbcnt_lo_u32_b32 v1, -1, 0
	v_mbcnt_hi_u32_b32 v1, -1, v1
	v_max3_f32 v0, v0, v15, v13
	v_lshlrev_b32_e32 v1, 2, v1
	v_max3_f32 v0, v0, v12, v21
	v_xor_b32_e32 v1, 0x80, v1
	ds_bpermute_b32 v1, v1, v0
	s_waitcnt lgkmcnt(0)
	v_max_f32_e32 v1, v1, v1
	v_max_f32_e32 v2, v0, v1
	v_mul_f32_e32 v206, 0xbfb8aa3b, v2
	v_fma_f32 v0, v144, s69, v206
	v_exp_f32_e32 v0, v0
	v_fma_f32 v1, v133, s69, v206
	v_exp_f32_e32 v1, v1
	v_add_f32_e32 v3, 0, v0
	s_nop 0
	v_add_f32_e32 v4, v1, v3
	v_fma_f32 v3, v134, s69, v206
	v_exp_f32_e32 v3, v3
	s_nop 1
	v_add_f32_e32 v5, v3, v4
	v_fma_f32 v4, v131, s69, v206
	v_exp_f32_e32 v4, v4
	s_nop 1
	v_add_f32_e32 v6, v4, v5
	v_fma_f32 v5, v130, s69, v206
	v_exp_f32_e32 v5, v5
	s_nop 1
	v_add_f32_e32 v7, v5, v6
	v_fma_f32 v6, v128, s69, v206
	v_exp_f32_e32 v6, v6
	s_nop 1
	v_add_f32_e32 v8, v6, v7
	v_fma_f32 v7, v126, s69, v206
	v_exp_f32_e32 v7, v7
	s_nop 1
	v_add_f32_e32 v9, v7, v8
	v_fma_f32 v8, v125, s69, v206
	v_exp_f32_e32 v8, v8
	s_nop 1
	v_add_f32_e32 v10, v8, v9
	v_fma_f32 v9, v124, s69, v206
	v_exp_f32_e32 v9, v9
	s_nop 1
	v_add_f32_e32 v11, v9, v10
	v_fma_f32 v10, v123, s69, v206
	v_exp_f32_e32 v10, v10
	s_nop 1
	v_add_f32_e32 v14, v10, v11
	v_fma_f32 v11, v122, s69, v206
	v_exp_f32_e32 v11, v11
	s_nop 1
	v_add_f32_e32 v17, v11, v14
	v_fma_f32 v14, v74, s69, v206
	v_exp_f32_e32 v14, v14
	s_nop 1
	v_add_f32_e32 v23, v14, v17
	v_fma_f32 v17, v72, s69, v206
	v_exp_f32_e32 v17, v17
	s_nop 1
	v_add_f32_e32 v24, v17, v23
	v_fma_f32 v23, v69, s69, v206
	v_exp_f32_e32 v23, v23
	s_nop 1
	v_add_f32_e32 v25, v23, v24
	v_fma_f32 v24, v65, s69, v206
	v_exp_f32_e32 v24, v24
	s_nop 1
	v_add_f32_e32 v26, v24, v25
	v_fma_f32 v25, v246, s69, v206
	v_exp_f32_e32 v25, v25
	s_nop 1
	v_add_f32_e32 v27, v25, v26
	v_fma_f32 v26, v251, s69, v206
	v_exp_f32_e32 v26, v26
	s_nop 1
	v_add_f32_e32 v28, v26, v27
	v_fma_f32 v27, v250, s69, v206
	v_exp_f32_e32 v27, v27
	s_nop 1
	v_add_f32_e32 v29, v27, v28
	v_fma_f32 v28, v249, s69, v206
	v_exp_f32_e32 v28, v28
	s_nop 1
	v_add_f32_e32 v30, v28, v29
	v_fma_f32 v29, v248, s69, v206
	v_exp_f32_e32 v29, v29
	s_nop 1
	v_add_f32_e32 v31, v29, v30
	v_fma_f32 v30, v247, s69, v206
	v_exp_f32_e32 v30, v30
	s_nop 1
	v_add_f32_e32 v44, v30, v31
	v_fma_f32 v31, v245, s69, v206
	v_exp_f32_e32 v31, v31
	s_nop 1
	v_add_f32_e32 v45, v31, v44
	v_fma_f32 v44, v244, s69, v206
	v_exp_f32_e32 v44, v44
	s_nop 1
	v_add_f32_e32 v46, v44, v45
	v_fma_f32 v45, v243, s69, v206
	v_exp_f32_e32 v45, v45
	s_nop 1
	v_add_f32_e32 v47, v45, v46
	v_fma_f32 v46, v241, s69, v206
	v_exp_f32_e32 v46, v46
	s_nop 1
	v_add_f32_e32 v56, v46, v47
	v_fma_f32 v47, v239, s69, v206
	v_exp_f32_e32 v47, v47
	s_nop 1
	v_add_f32_e32 v59, v47, v56
	v_fma_f32 v56, v145, s69, v206
	v_exp_f32_e32 v56, v56
	s_nop 1
	v_add_f32_e32 v60, v56, v59
	v_fma_f32 v59, v132, s69, v206
	v_exp_f32_e32 v59, v59
	s_nop 1
	v_add_f32_e32 v63, v59, v60
	v_fma_f32 v60, v127, s69, v206
	v_exp_f32_e32 v60, v60
	s_nop 1
	v_add_f32_e32 v65, v60, v63
	v_fma_f32 v63, v76, s69, v206
	v_exp_f32_e32 v63, v63
	s_nop 1
	v_add_f32_e32 v69, v63, v65
	v_fma_f32 v65, v68, s69, v206
	v_exp_f32_e32 v65, v65
	v_fma_f32 v68, v242, s69, v206
	v_exp_f32_e32 v68, v68
	v_add_f32_e32 v69, v65, v69
	s_nop 0
	v_add_f32_e32 v72, v68, v69
	v_fma_f32 v69, v240, s69, v206
	v_exp_f32_e32 v69, v69
	s_nop 1
	v_add_f32_e32 v74, v69, v72
	v_fma_f32 v72, v184, s69, v206
	v_exp_f32_e32 v72, v72
	s_nop 1
	v_add_f32_e32 v76, v72, v74
	v_fma_f32 v74, v135, s69, v206
	v_exp_f32_e32 v74, v74
	s_nop 1
	v_add_f32_e32 v120, v74, v76
	v_fma_f32 v76, v129, s69, v206
	v_exp_f32_e32 v76, v76
	s_nop 1
; __device__ __forceinline__ float fexp(float x) { return __builtin_amdgcn_exp2f(x * 1.44269504089f); }
; __device__ __forceinline__ float shfl_xor_(float v, int m) { return __builtin_bit_cast(float, __builtin_amdgcn_ds_bpermute((lane_id() ^ m) << 2, __builtin_bit_cast(int, v))); }
; __device__ __forceinline__ void phase_attn(const Frame& F, const Args& a) {
;     ...
; #pragma unroll
;         for (int kt = 0; kt < 5; ++kt)
; #pragma unroll
;             for (int e = 0; e < 16; ++e) { const float pv = (x[kt][e] > -1e29f) ? fexp(x[kt][e] - mx) : 0.f; x[kt][e] = pv; sum += pv; }
;         sum += shfl_xor_(sum, 32);
;         const float inv = 1.0f / sum;
;         if (hh == 0) { const size_t tok = (size_t)seq * SEQ + (size_t)(32 * qb + li) * d + p; LSE[((size_t)g * T + tok) * 4 + h] = mx + __builtin_amdgcn_logf(sum) * 0.69314718056f; }
	v_fma_f32 v78, v78, s69, v206
	v_exp_f32_e32 v78, v78
	v_add_f32_e32 v120, v76, v120
	v_add_f32_e32 v122, v78, v120
	v_fma_f32 v120, v121, s69, v206
	v_exp_f32_e32 v120, v120
	s_nop 1
	v_fma_f32 v79, v79, s69, v206
	v_exp_f32_e32 v79, v79
	v_add_f32_e32 v121, v120, v122
	v_mbcnt_lo_u32_b32 v122, -1, 0
	v_mbcnt_hi_u32_b32 v122, -1, v122
	v_fma_f32 v77, v77, s69, v206
	v_exp_f32_e32 v77, v77
	v_add_f32_e32 v121, v79, v121
	v_lshlrev_b32_e32 v122, 2, v122
	v_xor_b32_e32 v122, 0x80, v122
	v_fma_f32 v75, v75, s69, v206
	v_exp_f32_e32 v75, v75
	v_add_f32_e32 v121, v77, v121
	v_fma_f32 v73, v73, s69, v206
	v_exp_f32_e32 v73, v73
	v_add_f32_e32 v121, v75, v121
	v_fma_f32 v71, v71, s69, v206
	v_exp_f32_e32 v71, v71
	v_add_f32_e32 v121, v73, v121
	v_fma_f32 v70, v70, s69, v206
	v_exp_f32_e32 v70, v70
	v_add_f32_e32 v121, v71, v121
	v_fma_f32 v67, v67, s69, v206
	v_exp_f32_e32 v67, v67
	v_add_f32_e32 v121, v70, v121
	v_fma_f32 v66, v66, s69, v206
	v_exp_f32_e32 v66, v66
	v_add_f32_e32 v121, v67, v121
	v_fma_f32 v64, v64, s69, v206
	v_exp_f32_e32 v64, v64
	v_add_f32_e32 v121, v66, v121
	v_fma_f32 v62, v62, s69, v206
	v_exp_f32_e32 v62, v62
	v_add_f32_e32 v121, v64, v121
	v_fma_f32 v61, v61, s69, v206
	v_exp_f32_e32 v61, v61
	v_add_f32_e32 v121, v62, v121
	v_fma_f32 v58, v58, s69, v206
	v_exp_f32_e32 v58, v58
	v_add_f32_e32 v121, v61, v121
	v_fma_f32 v57, v57, s69, v206
	v_exp_f32_e32 v57, v57
	v_add_f32_e32 v121, v58, v121
	v_fma_f32 v55, v55, s69, v206
	v_exp_f32_e32 v55, v55
	v_add_f32_e32 v121, v57, v121
	v_fma_f32 v54, v54, s69, v206
	v_exp_f32_e32 v54, v54
	v_add_f32_e32 v121, v55, v121
	v_fma_f32 v53, v53, s69, v206
	v_exp_f32_e32 v53, v53
	v_add_f32_e32 v121, v54, v121
	v_fma_f32 v52, v52, s69, v206
	v_exp_f32_e32 v52, v52
	v_add_f32_e32 v121, v53, v121
	v_fma_f32 v51, v51, s69, v206
	v_exp_f32_e32 v51, v51
	v_add_f32_e32 v121, v52, v121
	v_fma_f32 v50, v50, s69, v206
	v_exp_f32_e32 v50, v50
	v_add_f32_e32 v121, v51, v121
	v_fma_f32 v49, v49, s69, v206
	v_exp_f32_e32 v49, v49
	v_add_f32_e32 v121, v50, v121
	v_fma_f32 v48, v48, s69, v206
	v_exp_f32_e32 v48, v48
	v_add_f32_e32 v121, v49, v121
	v_fma_f32 v43, v43, s69, v206
	v_exp_f32_e32 v43, v43
	v_add_f32_e32 v121, v48, v121
	v_fma_f32 v42, v42, s69, v206
	v_exp_f32_e32 v42, v42
	v_add_f32_e32 v121, v43, v121
	v_fma_f32 v41, v41, s69, v206
	v_exp_f32_e32 v41, v41
	v_add_f32_e32 v121, v42, v121
	v_fma_f32 v40, v40, s69, v206
	v_exp_f32_e32 v40, v40
	v_add_f32_e32 v121, v41, v121
	v_fma_f32 v38, v38, s69, v206
	v_exp_f32_e32 v38, v38
	v_add_f32_e32 v121, v40, v121
	v_fma_f32 v39, v39, s69, v206
	v_exp_f32_e32 v39, v39
	v_add_f32_e32 v121, v38, v121
	v_fma_f32 v37, v37, s69, v206
	v_exp_f32_e32 v37, v37
	v_add_f32_e32 v121, v39, v121
	v_fma_f32 v36, v36, s69, v206
	v_exp_f32_e32 v36, v36
	v_add_f32_e32 v121, v37, v121
	v_fma_f32 v35, v35, s69, v206
	v_exp_f32_e32 v35, v35
	v_add_f32_e32 v121, v36, v121
	v_fma_f32 v34, v34, s69, v206
	v_exp_f32_e32 v34, v34
	v_add_f32_e32 v121, v35, v121
	v_fma_f32 v33, v33, s69, v206
	v_exp_f32_e32 v33, v33
	v_add_f32_e32 v121, v34, v121
	v_fma_f32 v32, v32, s69, v206
	v_exp_f32_e32 v32, v32
	v_add_f32_e32 v121, v33, v121
	v_fma_f32 v22, v22, s69, v206
	v_exp_f32_e32 v22, v22
	v_add_f32_e32 v121, v32, v121
	v_fma_f32 v20, v20, s69, v206
	v_exp_f32_e32 v20, v20
	v_add_f32_e32 v121, v22, v121
	v_fma_f32 v19, v19, s69, v206
	v_exp_f32_e32 v19, v19
	v_add_f32_e32 v121, v20, v121
	v_fma_f32 v18, v18, s69, v206
	v_exp_f32_e32 v18, v18
	v_add_f32_e32 v121, v19, v121
	v_fma_f32 v16, v16, s69, v206
	v_exp_f32_e32 v16, v16
	v_add_f32_e32 v121, v18, v121
	v_fma_f32 v15, v15, s69, v206
	v_exp_f32_e32 v15, v15
	v_add_f32_e32 v121, v16, v121
	v_fma_f32 v13, v13, s69, v206
	v_exp_f32_e32 v13, v13
	v_add_f32_e32 v121, v15, v121
	v_fma_f32 v12, v12, s69, v206
	v_exp_f32_e32 v12, v12
	v_add_f32_e32 v121, v13, v121
	v_fma_f32 v21, v21, s69, v206
	v_exp_f32_e32 v21, v21
	v_add_f32_e32 v121, v12, v121
	v_add_f32_e32 v121, v21, v121
	ds_bpermute_b32 v122, v122, v121
	s_mov_b64 s[26:27], exec
	v_readlane_b32 s30, v255, 11
	v_readlane_b32 s31, v255, 12
	s_and_b64 s[30:31], s[26:27], s[30:31]
	s_xor_b64 s[26:27], s[30:31], s[26:27]
	s_mov_b64 exec, s[30:31]
	s_add_u32 s28, s9, s14
	s_addc_u32 s29, s8, s15
	s_or_b64 s[28:29], s[28:29], s[82:83]
	s_or_saveexec_b64 s[26:27], s[26:27]
	s_waitcnt lgkmcnt(0)
	v_add_f32_e32 v121, v121, v122
	v_mov_b64_e32 v[144:145], s[28:29]
	s_xor_b64 exec, exec, s[26:27]
	s_cbranch_execz .LBB0_1004
	v_log_f32_e32 v122, v121
	s_add_u32 s14, s9, s14
	v_or_b32_e32 v123, s5, v141
	s_addc_u32 s15, s8, s15
	v_lshlrev_b32_e32 v184, s4, v123
	s_or_b64 s[8:9], s[14:15], s[82:83]
	v_readlane_b32 s14, v255, 27
	v_fmac_f32_e32 v2, 0x3f317218, v122
	v_lshl_add_u64 v[122:123], s[8:9], 0, v[184:185]
	v_readlane_b32 s15, v255, 28
	s_lshl_b32 s82, s7, 2
	v_mov_b64_e32 v[144:145], s[8:9]
	v_lshl_add_u64 v[122:123], v[122:123], 4, s[14:15]
	v_lshl_add_u64 v[122:123], v[122:123], 0, s[82:83]
	global_store_dword v[122:123], v2, off
	s_branch .LBB0_1004
